# differential attention: waves 0-3 (older of each SIMD pair) issue the LDS-DMA pieces of both waves of the pair, waves 4-7 none
# speedup vs baseline: 1.0049x; 1.0049x over previous
.LBB0_449:
	s_ashr_i32 s79, s78, 31
	s_lshl_b64 s[2:3], s[78:79], 13
	v_or_b32_e32 v34, s34, v215
	v_or_b32_e32 v196, s2, v34
	v_mov_b32_e32 v197, s3
	v_lshlrev_b64 v[4:5], 12, v[196:197]
	s_lshl_b32 s57, s10, 7
	s_lshl_b32 s10, s10, 8
	v_lshl_add_u64 v[4:5], s[22:23], 0, v[4:5]
	v_lshl_add_u64 v[4:5], v[4:5], 0, s[10:11]
	s_mov_b32 s39, s11
	v_lshl_add_u64 v[4:5], v[4:5], 0, s[38:39]
	v_mov_b32_e32 v183, v153
	v_lshl_add_u64 v[4:5], v[4:5], 0, v[182:183]
	global_load_dwordx4 v[130:133], v[4:5], off
	global_load_dwordx4 v[134:137], v[4:5], off offset:32
	global_load_dwordx4 v[138:141], v[4:5], off offset:64
	global_load_dwordx4 v[142:145], v[4:5], off offset:96
	v_lshl_add_u64 v[2:3], s[2:3], 0, v[150:151]
	v_lshlrev_b64 v[2:3], 12, v[2:3]
	v_lshl_add_u64 v[2:3], s[22:23], 0, v[2:3]
	v_lshl_add_u64 v[2:3], v[2:3], 0, s[10:11]
	v_lshl_add_u64 v[202:203], v[2:3], 0, v[152:153]
	v_add_u32_e32 v0, s57, v216
	v_mov_b64_e32 v[2:3], s[28:29]
	v_mad_u64_u32 v[6:7], s[2:3], v0, s42, v[2:3]
	v_add_u32_e32 v0, s57, v217
	s_lshl_b64 s[2:3], s[78:79], 14
	v_mad_u64_u32 v[2:3], s[60:61], v0, s42, v[2:3]
	v_lshl_add_u64 v[6:7], v[6:7], 0, s[2:3]
	v_lshl_add_u64 v[2:3], v[2:3], 0, s[2:3]
	s_lshl_b32 s2, s48, 1
	v_mov_b32_e32 v181, v153
	s_sub_i32 s39, s2, s33
	s_lshl_b32 s2, s34, 12
	s_mov_b32 s3, s11
	v_mov_b32_e32 v179, v153
	v_lshl_add_u64 v[206:207], v[2:3], 0, v[180:181]
	v_lshl_add_u64 v[2:3], v[202:203], 0, s[2:3]
	s_mov_b32 m0, s7
	v_lshl_add_u64 v[204:205], v[6:7], 0, v[178:179]
	v_lshl_add_u64 v[6:7], v[2:3], 0, s[30:31]
	s_add_i32 s3, s7, 0x2000
	s_or_b32 s2, s34, 64
	global_load_lds_dwordx4 v[6:7], off
	v_lshl_add_u64 v[2:3], v[2:3], 0, s[36:37]
	s_mov_b32 m0, s3
	s_lshl_b32 s60, s2, 12
	s_mov_b32 s61, s11
	global_load_lds_dwordx4 v[2:3], off
	v_lshl_add_u64 v[2:3], v[202:203], 0, s[60:61]
	s_lshl_b32 s60, s33, 6
	s_add_i32 s5, s60, 0x80
	s_cmp_gt_i32 s39, 0
	s_cselect_b32 s62, s60, s5
	v_lshl_add_u64 v[6:7], v[2:3], 0, s[30:31]
	s_mov_b32 m0, s43
	s_ashr_i32 s63, s62, 31
	global_load_lds_dwordx4 v[6:7], off
	v_lshl_add_u64 v[2:3], v[2:3], 0, s[36:37]
	s_mov_b32 m0, s49
	s_lshl_b64 s[62:63], s[62:63], 12
	global_load_lds_dwordx4 v[2:3], off
	v_lshl_add_u64 v[2:3], v[202:203], 0, s[62:63]
	v_lshl_add_u64 v[6:7], v[2:3], 0, s[30:31]
	s_mov_b32 m0, s50
	v_lshl_add_u64 v[2:3], v[2:3], 0, s[36:37]
	global_load_lds_dwordx4 v[6:7], off
	s_mov_b32 m0, s51
	s_lshl_b32 s62, s34, 1
	s_mov_b32 s63, s11
	global_load_lds_dwordx4 v[2:3], off
	v_lshl_add_u64 v[44:45], v[204:205], 0, s[62:63]
	s_mov_b32 m0, s52
	v_lshl_add_u64 v[46:47], v[206:207], 0, s[62:63]
	global_load_lds_dwordx4 v[44:45], off
	s_mov_b32 m0, s53
	v_add_u32_e32 v35, v218, v149
	global_load_lds_dwordx4 v[46:47], off
	s_waitcnt vmcnt(6) lgkmcnt(0)
	s_barrier
	ds_read_b128 v[18:21], v35
	ds_read_b128 v[36:39], v35 offset:4096
	v_and_b32_e32 v155, 0x7fffffff, v1
	v_mov_b32_e32 v0, v201
	v_pk_mul_f32 v[16:17], v[170:171], v[0:1] op_sel_hi:[1,0] neg_lo:[0,1] neg_hi:[0,1]
	v_pk_mul_f32 v[14:15], v[168:169], v[0:1] op_sel_hi:[1,0] neg_lo:[0,1] neg_hi:[0,1]
	v_pk_mul_f32 v[12:13], v[166:167], v[0:1] op_sel_hi:[1,0] neg_lo:[0,1] neg_hi:[0,1]
	v_pk_mul_f32 v[10:11], v[164:165], v[0:1] op_sel_hi:[1,0] neg_lo:[0,1] neg_hi:[0,1]
	v_pk_mul_f32 v[8:9], v[162:163], v[0:1] op_sel_hi:[1,0] neg_lo:[0,1] neg_hi:[0,1]
	v_pk_mul_f32 v[6:7], v[158:159], v[0:1] op_sel_hi:[1,0] neg_lo:[0,1] neg_hi:[0,1]
	v_pk_mul_f32 v[4:5], v[156:157], v[0:1] op_sel_hi:[1,0] neg_lo:[0,1] neg_hi:[0,1]
	v_pk_mul_f32 v[2:3], v[154:155], v[0:1] op_sel_hi:[1,0] neg_lo:[0,1] neg_hi:[0,1]
	v_pk_mul_f32 v[32:33], v[192:193], v[0:1] op_sel_hi:[1,0] neg_lo:[0,1] neg_hi:[0,1]
	v_pk_mul_f32 v[30:31], v[190:191], v[0:1] op_sel_hi:[1,0] neg_lo:[0,1] neg_hi:[0,1]
	s_waitcnt vmcnt(0) lgkmcnt(0)
	v_mfma_f32_32x32x16_bf16 v[2:17], v[18:21], v[130:133], v[2:17]
	v_mul_f32_e64 v28, v188, -v0
	v_mul_f32_e64 v29, v189, -v0
	v_mul_f32_e64 v26, v186, -v0
	v_mul_f32_e64 v27, v187, -v0
	v_mul_f32_e64 v24, v184, -v0
	v_mul_f32_e64 v25, v185, -v0
	v_pk_mul_f32 v[22:23], v[176:177], v[0:1] op_sel_hi:[1,0] neg_lo:[0,1] neg_hi:[0,1]
	v_pk_mul_f32 v[20:21], v[174:175], v[0:1] op_sel_hi:[1,0] neg_lo:[0,1] neg_hi:[0,1]
	v_pk_mul_f32 v[18:19], v[172:173], v[0:1] op_sel_hi:[1,0] neg_lo:[0,1] neg_hi:[0,1]
	v_add_u32_e32 v48, v218, v208
	v_add_u32_e32 v49, v218, v209
	v_mfma_f32_32x32x16_bf16 v[18:33], v[36:39], v[130:133], v[18:33]
	ds_read_b128 v[36:39], v48
	ds_read_b128 v[40:43], v48 offset:4096
	v_add_u32_e32 v50, v218, v226
	s_sub_i32 s48, s4, s33
	s_cmp_gt_i32 s39, 1
	s_cselect_b32 s4, 1, 3
	s_add_i32 s4, s4, s33
	s_lshl_b32 s4, s4, 6
	s_waitcnt lgkmcnt(1)
	v_mfma_f32_32x32x16_bf16 v[2:17], v[36:39], v[134:137], v[2:17]
	s_ashr_i32 s5, s4, 31
	s_lshl_b64 s[4:5], s[4:5], 12
	s_mov_b32 m0, s7
	s_mov_b32 s10, 0
	s_waitcnt lgkmcnt(0)
	v_mfma_f32_32x32x16_bf16 v[18:33], v[40:43], v[134:137], v[18:33]
	ds_read_b128 v[36:39], v49
	ds_read_b128 v[40:43], v49 offset:4096
	s_waitcnt lgkmcnt(1)
	v_mfma_f32_32x32x16_bf16 v[2:17], v[36:39], v[138:141], v[2:17]
	ds_read_b128 v[36:39], v50
	s_waitcnt lgkmcnt(1)
	v_mfma_f32_32x32x16_bf16 v[18:33], v[40:43], v[138:141], v[18:33]
	ds_read_b128 v[40:43], v50 offset:4096
	s_waitcnt vmcnt(4) lgkmcnt(0)
	s_barrier
	s_waitcnt lgkmcnt(1)
	v_mfma_f32_32x32x16_bf16 v[2:17], v[36:39], v[142:145], v[2:17]
	s_waitcnt lgkmcnt(0)
	v_mfma_f32_32x32x16_bf16 v[18:33], v[40:43], v[142:145], v[18:33]
	s_cmp_lg_u32 s100, 0
	s_cbranch_scc1 .Lattn_dma_pro
	v_lshl_add_u64 v[36:37], v[202:203], 0, s[4:5]
	v_lshl_add_u64 v[38:39], v[36:37], 0, s[30:31]
	global_load_lds_dwordx4 v[38:39], off
	v_lshl_add_u64 v[36:37], v[36:37], 0, s[36:37]
	s_mov_b32 m0, s3
	s_mov_b32 s84, 0x20000
	global_load_lds_dwordx4 v[36:37], off
	s_mov_b32 s85, 0
	s_add_i32 m0, s7, 0x1000
	v_lshl_add_u64 v[38:39], v[38:39], 0, s[84:85]
	global_load_lds_dwordx4 v[38:39], off
	s_add_i32 m0, s3, 0x1000
	v_lshl_add_u64 v[36:37], v[36:37], 0, s[84:85]
	global_load_lds_dwordx4 v[36:37], off
	s_mov_b32 s84, 0xc00000
	v_lshl_add_u64 v[36:37], v[44:45], 0, s[40:41]
	s_mov_b32 m0, s54
	v_lshl_add_u64 v[38:39], v[46:47], 0, s[40:41]
	global_load_lds_dwordx4 v[36:37], off
	s_mov_b32 m0, s55
	s_nop 0
	global_load_lds_dwordx4 v[38:39], off
	s_add_i32 m0, s54, 0x2000
	v_lshl_add_u64 v[36:37], v[36:37], 0, s[84:85]
	global_load_lds_dwordx4 v[36:37], off
	s_add_i32 m0, s55, 0x2000
	v_lshl_add_u64 v[38:39], v[38:39], 0, s[84:85]
	global_load_lds_dwordx4 v[38:39], off
.Lattn_dma_pro:
	v_or_b32_e32 v38, s2, v148
	s_nop 15
	v_max3_f32 v36, v2, v3, v18
	v_max3_f32 v37, v4, v5, v19
	s_nop 15
	s_nop 15
	s_nop 15
	s_nop 0
	v_max3_f32 v36, v36, v20, v21
	v_max3_f32 v37, v37, v8, v9
	s_nop 0
	v_max3_f32 v36, v36, v6, v7
	v_max3_f32 v37, v37, v24, v25
	s_nop 0
	v_max3_f32 v36, v36, v22, v23
	v_max3_f32 v37, v37, v12, v13
	s_nop 0
	v_max3_f32 v36, v36, v10, v11
	v_max3_f32 v37, v37, v28, v29
	s_nop 0
	v_max3_f32 v36, v36, v26, v27
	v_max3_f32 v37, v37, v16, v17
	s_nop 0
	v_max3_f32 v36, v36, v14, v15
	v_max3_f32 v37, v37, v32, v33
	s_nop 0
	v_max3_f32 v36, v36, v30, v31
	s_nop 0
	v_max_f32_e32 v36, v36, v37
	s_nop 0
	v_mov_b32_e32 v37, v36
	s_nop 1
	v_permlane32_swap_b32 v36, v37
	s_nop 1
	s_nop 0
	v_max_f32_e32 v37, v37, v37
	v_max_f32_e32 v36, v36, v36
	v_max_f32_e32 v37, v36, v37
	v_sub_f32_e32 v2, v2, v37
	v_sub_f32_e32 v18, v18, v37
	v_sub_f32_e32 v3, v3, v37
	v_sub_f32_e32 v19, v19, v37
	v_sub_f32_e32 v4, v4, v37
	v_sub_f32_e32 v20, v20, v37
	v_sub_f32_e32 v5, v5, v37
	v_sub_f32_e32 v21, v21, v37
	v_sub_f32_e32 v6, v6, v37
	v_sub_f32_e32 v22, v22, v37
	v_sub_f32_e32 v7, v7, v37
	v_sub_f32_e32 v23, v23, v37
	v_sub_f32_e32 v8, v8, v37
	v_sub_f32_e32 v24, v24, v37
	v_sub_f32_e32 v9, v9, v37
	v_sub_f32_e32 v25, v25, v37
	v_sub_f32_e32 v10, v10, v37
	v_sub_f32_e32 v26, v26, v37
	v_sub_f32_e32 v11, v11, v37
	v_sub_f32_e32 v27, v27, v37
	v_sub_f32_e32 v12, v12, v37
	v_sub_f32_e32 v28, v28, v37
	v_sub_f32_e32 v13, v13, v37
	v_sub_f32_e32 v29, v29, v37
	v_sub_f32_e32 v14, v14, v37
	v_sub_f32_e32 v30, v30, v37
	v_sub_f32_e32 v15, v15, v37
	v_sub_f32_e32 v31, v31, v37
	v_sub_f32_e32 v16, v16, v37
	v_sub_f32_e32 v32, v32, v37
	v_sub_f32_e32 v17, v17, v37
	v_sub_f32_e32 v33, v33, v37
	v_exp_f32_e32 v52, v2
	v_exp_f32_e32 v53, v18
	v_exp_f32_e32 v54, v3
	v_exp_f32_e32 v55, v19
	v_exp_f32_e32 v56, v4
	v_exp_f32_e32 v57, v20
	v_exp_f32_e32 v58, v5
	v_exp_f32_e32 v59, v21
	v_exp_f32_e32 v60, v6
	v_exp_f32_e32 v61, v22
	v_exp_f32_e32 v62, v7
	v_exp_f32_e32 v63, v23
	v_exp_f32_e32 v64, v8
	v_exp_f32_e32 v65, v24
	v_exp_f32_e32 v101, v9
	v_exp_f32_e32 v102, v25
	v_exp_f32_e32 v103, v10
	v_exp_f32_e32 v104, v26
	v_exp_f32_e32 v114, v27
	v_exp_f32_e32 v105, v11
	v_exp_f32_e32 v107, v12
	v_exp_f32_e32 v115, v28
	v_exp_f32_e32 v108, v13
	v_exp_f32_e32 v116, v29
	v_exp_f32_e32 v109, v14
	v_exp_f32_e32 v117, v30
	ds_read_b128 v[10:13], v35 offset:16384
	v_exp_f32_e32 v118, v15
	v_exp_f32_e32 v119, v31
	ds_read_b128 v[2:5], v35 offset:20480
	v_exp_f32_e32 v35, v16
	v_exp_f32_e32 v120, v32
	ds_read_b128 v[6:9], v48 offset:16384
	v_exp_f32_e32 v121, v17
	v_exp_f32_e32 v122, v33
	ds_read_b128 v[14:17], v48 offset:20480
	ds_read_b128 v[18:21], v49 offset:16384
	ds_read_b128 v[22:25], v49 offset:20480
	ds_read_b128 v[26:29], v50 offset:16384
	ds_read_b128 v[30:33], v50 offset:20480
	v_add_f32_e32 v36, 0, v52
	v_add_f32_e32 v36, v53, v36
	v_add_f32_e32 v36, v54, v36
	v_add_f32_e32 v36, v55, v36
	v_add_f32_e32 v36, v56, v36
	v_add_f32_e32 v36, v57, v36
	v_add_f32_e32 v36, v58, v36
	v_add_f32_e32 v36, v59, v36
	v_add_f32_e32 v36, v60, v36
	v_add_f32_e32 v36, v61, v36
	v_add_f32_e32 v36, v62, v36
	v_add_f32_e32 v36, v63, v36
	v_add_f32_e32 v36, v64, v36
	v_add_f32_e32 v36, v65, v36
	v_add_f32_e32 v36, v101, v36
	v_add_f32_e32 v36, v102, v36
	v_add_f32_e32 v36, v103, v36
	v_add_f32_e32 v36, v104, v36
	v_add_f32_e32 v36, v105, v36
	v_add_f32_e32 v36, v114, v36
	v_add_f32_e32 v36, v107, v36
	v_add_f32_e32 v36, v115, v36
	v_add_f32_e32 v36, v108, v36
	v_add_f32_e32 v36, v116, v36
	v_add_f32_e32 v36, v109, v36
	v_add_f32_e32 v36, v117, v36
	v_add_f32_e32 v36, v118, v36
	v_add_f32_e32 v36, v119, v36
	v_add_f32_e32 v36, v35, v36
	v_add_f32_e32 v36, v120, v36
	v_add_f32_e32 v36, v121, v36
	v_add_f32_e32 v36, v122, v36
	v_sub_u32_e32 v82, v34, v38
	v_pk_add_f32 v[198:199], v[36:37], 0 op_sel_hi:[1,0]
	v_add_u32_e32 v36, -1, v82
	v_add_u32_e32 v37, -3, v82
	v_add_u32_e32 v38, -2, v82
	v_add_u32_e32 v39, -5, v82
	v_add_u32_e32 v40, -4, v82
	v_add_u32_e32 v41, -7, v82
	v_add_u32_e32 v42, -6, v82
	v_subrev_u32_e32 v43, 17, v82
	v_add_u32_e32 v44, -16, v82
	v_subrev_u32_e32 v45, 19, v82
	v_subrev_u32_e32 v46, 18, v82
	v_subrev_u32_e32 v47, 21, v82
	v_subrev_u32_e32 v48, 20, v82
	v_subrev_u32_e32 v49, 23, v82
	v_subrev_u32_e32 v50, 22, v82
	v_cvt_f32_i32_e32 v50, v50
	v_cvt_f32_i32_e32 v51, v49
	v_cvt_f32_i32_e32 v48, v48
	v_cvt_f32_i32_e32 v49, v47
	v_cvt_f32_i32_e32 v46, v46
	v_cvt_f32_i32_e32 v47, v45
	v_cvt_f32_i32_e32 v44, v44
	v_cvt_f32_i32_e32 v45, v43
	v_cvt_f32_i32_e32 v42, v42
	v_cvt_f32_i32_e32 v43, v41
	v_cvt_f32_i32_e32 v40, v40
	v_cvt_f32_i32_e32 v41, v39
	v_cvt_f32_i32_e32 v39, v82
	v_cvt_f32_i32_e32 v66, v36
	v_cvt_f32_i32_e32 v67, v37
	v_cvt_f32_i32_e32 v38, v38
	v_and_b32_e32 v36, 0x7fffffff, v39
	v_and_b32_e32 v37, 0x7fffffff, v66
	v_and_b32_e32 v39, 0x7fffffff, v67
	v_and_b32_e32 v38, 0x7fffffff, v38
	v_and_b32_e32 v41, 0x7fffffff, v41
	v_and_b32_e32 v40, 0x7fffffff, v40
	v_and_b32_e32 v43, 0x7fffffff, v43
	v_and_b32_e32 v42, 0x7fffffff, v42
	v_and_b32_e32 v45, 0x7fffffff, v45
	v_and_b32_e32 v44, 0x7fffffff, v44
	v_and_b32_e32 v47, 0x7fffffff, v47
	v_and_b32_e32 v46, 0x7fffffff, v46
	v_and_b32_e32 v49, 0x7fffffff, v49
	v_and_b32_e32 v48, 0x7fffffff, v48
	v_and_b32_e32 v51, 0x7fffffff, v51
	v_and_b32_e32 v50, 0x7fffffff, v50
	v_pk_fma_f32 v[80:81], v[0:1], v[50:51], v[198:199] op_sel:[0,0,1] op_sel_hi:[0,1,1] neg_lo:[1,0,1] neg_hi:[1,0,1]
	v_pk_fma_f32 v[78:79], v[0:1], v[48:49], v[198:199] op_sel:[0,0,1] op_sel_hi:[0,1,1] neg_lo:[1,0,1] neg_hi:[1,0,1]
	v_pk_fma_f32 v[76:77], v[0:1], v[46:47], v[198:199] op_sel:[0,0,1] op_sel_hi:[0,1,1] neg_lo:[1,0,1] neg_hi:[1,0,1]
	v_pk_fma_f32 v[74:75], v[0:1], v[44:45], v[198:199] op_sel:[0,0,1] op_sel_hi:[0,1,1] neg_lo:[1,0,1] neg_hi:[1,0,1]
	v_pk_fma_f32 v[72:73], v[0:1], v[42:43], v[198:199] op_sel:[0,0,1] op_sel_hi:[0,1,1] neg_lo:[1,0,1] neg_hi:[1,0,1]
	v_pk_fma_f32 v[70:71], v[0:1], v[40:41], v[198:199] op_sel:[0,0,1] op_sel_hi:[0,1,1] neg_lo:[1,0,1] neg_hi:[1,0,1]
	v_pk_fma_f32 v[68:69], v[0:1], v[38:39], v[198:199] op_sel:[0,0,1] op_sel_hi:[0,1,1] neg_lo:[1,0,1] neg_hi:[1,0,1]
	v_pk_fma_f32 v[66:67], v[0:1], v[36:37], v[198:199] op_sel:[0,0,1] op_sel_hi:[0,1,1] neg_lo:[1,0,1] neg_hi:[1,0,1]
	v_subrev_u32_e32 v36, 33, v82
	v_subrev_u32_e32 v37, 32, v82
	v_subrev_u32_e32 v38, 35, v82
	v_subrev_u32_e32 v39, 34, v82
	v_subrev_u32_e32 v40, 37, v82
	v_subrev_u32_e32 v41, 36, v82
	v_subrev_u32_e32 v42, 39, v82
	v_subrev_u32_e32 v43, 38, v82
	v_subrev_u32_e32 v44, 49, v82
	v_subrev_u32_e32 v45, 48, v82
	v_subrev_u32_e32 v46, 51, v82
	v_subrev_u32_e32 v47, 50, v82
	v_subrev_u32_e32 v48, 53, v82
	v_subrev_u32_e32 v49, 52, v82
	v_subrev_u32_e32 v50, 55, v82
	v_subrev_u32_e32 v51, 54, v82
	v_cvt_f32_i32_e32 v82, v51
	v_cvt_f32_i32_e32 v50, v50
	v_cvt_f32_i32_e32 v51, v49
	v_cvt_f32_i32_e32 v48, v48
	v_cvt_f32_i32_e32 v49, v47
	v_cvt_f32_i32_e32 v46, v46
	v_cvt_f32_i32_e32 v47, v45
	v_cvt_f32_i32_e32 v44, v44
	v_cvt_f32_i32_e32 v45, v43
	v_cvt_f32_i32_e32 v42, v42
	v_cvt_f32_i32_e32 v43, v41
	v_cvt_f32_i32_e32 v40, v40
	v_cvt_f32_i32_e32 v36, v36
	v_cvt_f32_i32_e32 v41, v37
	v_cvt_f32_i32_e32 v38, v38
	v_cvt_f32_i32_e32 v83, v39
	v_and_b32_e32 v37, 0x7fffffff, v36
	v_and_b32_e32 v36, 0x7fffffff, v41
	v_and_b32_e32 v39, 0x7fffffff, v38
	v_and_b32_e32 v38, 0x7fffffff, v83
	v_and_b32_e32 v41, 0x7fffffff, v40
	v_and_b32_e32 v40, 0x7fffffff, v43
	v_and_b32_e32 v43, 0x7fffffff, v42
	v_and_b32_e32 v42, 0x7fffffff, v45
	v_and_b32_e32 v45, 0x7fffffff, v44
	v_and_b32_e32 v44, 0x7fffffff, v47
	v_and_b32_e32 v47, 0x7fffffff, v46
	v_and_b32_e32 v46, 0x7fffffff, v49
	v_and_b32_e32 v49, 0x7fffffff, v48
	v_and_b32_e32 v48, 0x7fffffff, v51
	v_and_b32_e32 v51, 0x7fffffff, v50
	v_and_b32_e32 v50, 0x7fffffff, v82
	v_pk_fma_f32 v[96:97], v[0:1], v[50:51], v[198:199] op_sel:[0,0,1] op_sel_hi:[0,1,1] neg_lo:[1,0,1] neg_hi:[1,0,1]
	v_pk_fma_f32 v[94:95], v[0:1], v[48:49], v[198:199] op_sel:[0,0,1] op_sel_hi:[0,1,1] neg_lo:[1,0,1] neg_hi:[1,0,1]
	v_pk_fma_f32 v[92:93], v[0:1], v[46:47], v[198:199] op_sel:[0,0,1] op_sel_hi:[0,1,1] neg_lo:[1,0,1] neg_hi:[1,0,1]
	v_pk_fma_f32 v[90:91], v[0:1], v[44:45], v[198:199] op_sel:[0,0,1] op_sel_hi:[0,1,1] neg_lo:[1,0,1] neg_hi:[1,0,1]
	v_pk_fma_f32 v[88:89], v[0:1], v[42:43], v[198:199] op_sel:[0,0,1] op_sel_hi:[0,1,1] neg_lo:[1,0,1] neg_hi:[1,0,1]
	v_pk_fma_f32 v[86:87], v[0:1], v[40:41], v[198:199] op_sel:[0,0,1] op_sel_hi:[0,1,1] neg_lo:[1,0,1] neg_hi:[1,0,1]
	v_pk_fma_f32 v[84:85], v[0:1], v[38:39], v[198:199] op_sel:[0,0,1] op_sel_hi:[0,1,1] neg_lo:[1,0,1] neg_hi:[1,0,1]
	v_pk_fma_f32 v[82:83], v[0:1], v[36:37], v[198:199] op_sel:[0,0,1] op_sel_hi:[0,1,1] neg_lo:[1,0,1] neg_hi:[1,0,1]
	s_waitcnt lgkmcnt(0)
	v_mfma_f32_32x32x16_bf16 v[66:81], v[10:13], v[130:133], v[66:81]
	v_cvt_pk_bf16_f32 v98, v52, v54
	v_cvt_pk_bf16_f32 v99, v56, v58
	v_cvt_pk_bf16_f32 v100, v60, v62
	v_cvt_pk_bf16_f32 v101, v64, v101
	v_cvt_pk_bf16_f32 v110, v53, v55
	v_cvt_pk_bf16_f32 v111, v57, v59
	v_cvt_pk_bf16_f32 v112, v61, v63
	v_mfma_f32_32x32x16_bf16 v[82:97], v[2:5], v[130:133], v[82:97]
	v_cvt_pk_bf16_f32 v113, v65, v102
	v_cvt_pk_bf16_f32 v106, v103, v105
	v_cvt_pk_bf16_f32 v107, v107, v108
	v_cvt_pk_bf16_f32 v108, v109, v118
	v_cvt_pk_bf16_f32 v109, v35, v121
	v_cvt_pk_bf16_f32 v114, v104, v114
	v_cvt_pk_bf16_f32 v115, v115, v116
	v_mfma_f32_32x32x16_bf16 v[66:81], v[6:9], v[134:137], v[66:81]
	v_cvt_pk_bf16_f32 v116, v117, v119
	s_cmp_lt_i32 s48, 2
	v_cvt_pk_bf16_f32 v117, v120, v122
	v_mfma_f32_32x32x16_bf16 v[82:97], v[14:17], v[134:137], v[82:97]
	v_mfma_f32_32x32x16_bf16 v[66:81], v[18:21], v[138:141], v[66:81]
	v_mfma_f32_32x32x16_bf16 v[82:97], v[22:25], v[138:141], v[82:97]
	v_mfma_f32_32x32x16_bf16 v[66:81], v[26:29], v[142:145], v[66:81]
	v_mfma_f32_32x32x16_bf16 v[82:97], v[30:33], v[142:145], v[82:97]
	s_cbranch_scc1 .LBB0_472
	v_sub_u32_e32 v0, v148, v34
	v_cvt_f32_i32_e32 v155, v0
	v_mov_b32_e32 v16, v153
	v_mov_b32_e32 v17, v153
	v_mov_b32_e32 v2, v153
	v_mov_b32_e32 v3, v153
	v_mov_b32_e32 v4, v153
	v_mov_b32_e32 v5, v153
	v_mov_b32_e32 v6, v153
	v_mov_b32_e32 v7, v153
	v_mov_b32_e32 v8, v153
	v_mov_b32_e32 v9, v153
	v_mov_b32_e32 v10, v153
	v_mov_b32_e32 v11, v153
	v_mov_b32_e32 v12, v153
	v_mov_b32_e32 v13, v153
	v_mov_b32_e32 v14, v153
	v_mov_b32_e32 v15, v153
	v_mov_b64_e32 v[32:33], v[16:17]
	v_mov_b64_e32 v[48:49], v[16:17]
	v_mov_b64_e32 v[64:65], v[16:17]
	s_mov_b64 s[2:3], 0
	v_mov_b32_e32 v0, 1.0
	s_mov_b32 s62, 2
	s_mov_b32 s34, 5
	v_mov_b64_e32 v[30:31], v[14:15]
	v_mov_b64_e32 v[28:29], v[12:13]
	v_mov_b64_e32 v[26:27], v[10:11]
	v_mov_b64_e32 v[24:25], v[8:9]
	v_mov_b64_e32 v[22:23], v[6:7]
	v_mov_b64_e32 v[20:21], v[4:5]
	v_mov_b64_e32 v[18:19], v[2:3]
	v_mov_b64_e32 v[46:47], v[14:15]
	v_mov_b64_e32 v[44:45], v[12:13]
	v_mov_b64_e32 v[42:43], v[10:11]
	v_mov_b64_e32 v[40:41], v[8:9]
	v_mov_b64_e32 v[38:39], v[6:7]
	v_mov_b64_e32 v[36:37], v[4:5]
	v_mov_b64_e32 v[34:35], v[2:3]
	v_mov_b64_e32 v[62:63], v[14:15]
	v_mov_b64_e32 v[60:61], v[12:13]
	v_mov_b64_e32 v[58:59], v[10:11]
	v_mov_b64_e32 v[56:57], v[8:9]
	v_mov_b64_e32 v[54:55], v[6:7]
	v_mov_b64_e32 v[52:53], v[4:5]
	v_mov_b64_e32 v[50:51], v[2:3]
	s_add_i32 s61, s34, -2
	s_cmp_gt_i32 s61, s48
	s_mov_b64 s[4:5], -1
	s_cbranch_scc0 .LBB0_468

.Lattn_A_fast:
	s_lshl_b32 s80, s10, 14
	v_add_u32_e32 v179, s80, v219
	v_add_u32_e32 v126, v179, v149
	ds_read_b128 v[102:105], v126 offset:49152
	ds_read_b128 v[118:121], v126 offset:53248
	ds_read_b128 v[122:125], v126 offset:57344
	ds_read_b128 v[228:231], v126 offset:61440
	s_add_i32 s78, s34, -1
	s_add_i32 s63, s60, 0x80
	s_lshl_b32 s79, s62, 14
	s_cmp_gt_i32 s78, s48
	s_cselect_b32 s4, 0, 1
	s_waitcnt lgkmcnt(2)
	v_mfma_f32_32x32x16_bf16 v[50:65], v[102:105], v[98:101], v[50:65]
	v_exp_f32_e32 v66, v66
	v_exp_f32_e32 v249, v82
	v_add_u32_e32 v181, v179, v208
	ds_read_b128 v[102:105], v181 offset:49152
	v_mfma_f32_32x32x16_bf16 v[34:49], v[118:121], v[98:101], v[34:49]
	v_add_f32_e32 v254, 0, v66
	v_add_f32_e32 v255, 0, v249
	v_exp_f32_e32 v67, v67
	v_exp_f32_e32 v250, v83
	ds_read_b128 v[232:235], v181 offset:53248
	s_waitcnt lgkmcnt(2)
	v_mfma_f32_32x32x16_bf16 v[18:33], v[122:125], v[98:101], v[18:33]
	v_add_f32_e32 v254, v67, v254
	v_add_f32_e32 v255, v250, v255
	v_exp_f32_e32 v68, v68
	v_exp_f32_e32 v195, v84
	ds_read_b128 v[126:129], v181 offset:57344
	v_mfma_f32_32x32x16_bf16 v[2:17], v[228:231], v[98:101], v[2:17]
	v_add_f32_e32 v254, v68, v254
	v_add_f32_e32 v255, v195, v255
	v_exp_f32_e32 v69, v69
	v_exp_f32_e32 v251, v85
	ds_read_b128 v[118:121], v181 offset:61440
	s_waitcnt lgkmcnt(2)
	v_mfma_f32_32x32x16_bf16 v[50:65], v[102:105], v[106:109], v[50:65]
	v_add_f32_e32 v254, v69, v254
	v_add_f32_e32 v255, v251, v255
	v_exp_f32_e32 v70, v70
	v_exp_f32_e32 v252, v86
	v_add_u32_e32 v181, v179, v209
	ds_read_b128 v[122:125], v181 offset:49152
	v_mfma_f32_32x32x16_bf16 v[34:49], v[232:235], v[106:109], v[34:49]
	s_add_i32 s78, s34, -4
	s_cmp_gt_i32 s78, s39
	s_cselect_b64 vcc, -1, 0
	s_cselect_b32 s82, s63, s60
	v_cndmask_b32_e64 v200, v201, -v201, vcc
	s_cmp_lg_u32 s100, 0
	s_cbranch_scc1 .Lattn_dma_a
	s_lshl_b32 s84, s82, 1
	s_mov_b32 s85, 0
	s_addk_i32 s80, 0xc000
	s_cmp_lg_u32 s10, 0
	s_cselect_b32 s80, s80, 0x8000
	s_add_i32 s80, s14, s80
	v_lshl_add_u64 v[98:99], v[204:205], 0, s[84:85]
	s_add_i32 m0, s80, 0xc000
	v_lshl_add_u64 v[100:101], v[206:207], 0, s[84:85]
	global_load_lds_dwordx4 v[98:99], off
	s_add_i32 m0, s80, 0xc400
	s_mov_b32 s84, 0xc00000
	global_load_lds_dwordx4 v[100:101], off
	s_add_i32 m0, s80, 0xe000
	v_lshl_add_u64 v[98:99], v[98:99], 0, s[84:85]
	global_load_lds_dwordx4 v[98:99], off
	s_add_i32 m0, s80, 0xe400
	v_lshl_add_u64 v[100:101], v[100:101], 0, s[84:85]
	global_load_lds_dwordx4 v[100:101], off
	s_cmp_lg_u32 s4, 0
	s_cbranch_scc0 .Lattn_dma_a
	s_add_i32 s81, s60, 0x100
	s_cmp_le_i32 s61, s39
	s_cselect_b32 s84, s63, s81
	s_lshl_b32 s84, s84, 12
	s_add_i32 s81, s79, 0xffffc000
	s_cmp_lg_u32 s62, 0
	s_cselect_b32 s81, s81, 0x8000
	v_lshl_add_u64 v[98:99], v[202:203], 0, s[84:85]
	s_add_i32 s81, s7, s81
	s_mov_b32 m0, s81
	v_lshl_add_u64 v[100:101], v[98:99], 0, s[30:31]
	global_load_lds_dwordx4 v[100:101], off
	s_add_i32 m0, s81, 0x2000
	v_lshl_add_u64 v[98:99], v[98:99], 0, s[36:37]
	global_load_lds_dwordx4 v[98:99], off
	s_mov_b32 s84, 0x20000
	s_add_i32 m0, s81, 0x1000
	v_lshl_add_u64 v[100:101], v[100:101], 0, s[84:85]
	global_load_lds_dwordx4 v[100:101], off
	s_add_i32 m0, s81, 0x3000
	v_lshl_add_u64 v[98:99], v[98:99], 0, s[84:85]
	global_load_lds_dwordx4 v[98:99], off
.Lattn_dma_a:
	v_cvt_f32_i32_e32 v98, s82
	v_add_u32_e32 v183, s79, v218
	v_add_f32_e32 v98, v155, v98
	v_fma_f32 v224, v200, v98, -v199
	v_fma_f32 v98, 0, v200, v224
	v_add_f32_e32 v99, v200, v224
	v_fma_f32 v100, v200, s64, v224
	v_fma_f32 v101, v200, s65, v224
	v_fma_f32 v102, v200, s66, v224
	v_fma_f32 v103, v200, s67, v224
	v_mul_f32_e32 v240, 0x42000000, v200
	ds_read_b128 v[228:231], v181 offset:53248
	s_waitcnt lgkmcnt(2)
	v_mfma_f32_32x32x16_bf16 v[18:33], v[126:129], v[106:109], v[18:33]
	v_add_f32_e32 v254, v70, v254
	v_add_f32_e32 v255, v252, v255
	v_exp_f32_e32 v71, v71
	v_fma_f32 v104, v200, s68, v224
	v_fma_f32 v105, v200, s69, v224
	ds_read_b128 v[126:129], v181 offset:57344
	v_mfma_f32_32x32x16_bf16 v[2:17], v[118:121], v[106:109], v[2:17]
	s_setprio 0
	v_add_f32_e32 v254, v71, v254
	v_exp_f32_e32 v253, v87
	v_exp_f32_e32 v82, v72
	ds_read_b128 v[118:121], v181 offset:61440
	s_waitcnt lgkmcnt(2)
	v_mfma_f32_32x32x16_bf16 v[50:65], v[122:125], v[110:113], v[50:65]
	v_add_f32_e32 v255, v253, v255
	v_add_f32_e32 v254, v82, v254
	v_exp_f32_e32 v72, v88
	v_fma_f32 v106, v200, s70, v224
	v_fma_f32 v107, v200, s71, v224
	v_add_u32_e32 v179, v179, v226
	ds_read_b128 v[122:125], v179 offset:49152
	v_mfma_f32_32x32x16_bf16 v[34:49], v[228:231], v[110:113], v[34:49]
	v_add_f32_e32 v255, v72, v255
	v_exp_f32_e32 v83, v73
	v_exp_f32_e32 v73, v89
	ds_read_b128 v[228:231], v179 offset:53248
	s_waitcnt lgkmcnt(2)
	v_mfma_f32_32x32x16_bf16 v[18:33], v[126:129], v[110:113], v[18:33]
	v_add_f32_e32 v254, v83, v254
	v_add_f32_e32 v255, v73, v255
	v_exp_f32_e32 v74, v74
	v_fma_f32 v108, v200, s72, v224
	v_fma_f32 v109, v200, s73, v224
	ds_read_b128 v[126:129], v179 offset:57344
	v_mfma_f32_32x32x16_bf16 v[2:17], v[118:121], v[110:113], v[2:17]
	v_add_f32_e32 v254, v74, v254
	v_exp_f32_e32 v90, v90
	v_exp_f32_e32 v75, v75
	ds_read_b128 v[118:121], v179 offset:61440
	s_waitcnt lgkmcnt(2)
	v_mfma_f32_32x32x16_bf16 v[50:65], v[122:125], v[114:117], v[50:65]
	v_add_f32_e32 v255, v90, v255
	v_add_f32_e32 v254, v75, v254
	v_exp_f32_e32 v91, v91
	v_fma_f32 v110, v200, s74, v224
	v_fma_f32 v111, v200, s75, v224
	v_add_u32_e32 v112, v183, v149
	ds_read_b128 v[232:235], v112
	v_mfma_f32_32x32x16_bf16 v[34:49], v[228:231], v[114:117], v[34:49]
	v_add_f32_e32 v255, v91, v255
	v_exp_f32_e32 v76, v76
	v_exp_f32_e32 v92, v92
	ds_read_b128 v[228:231], v112 offset:4096
	s_waitcnt lgkmcnt(2)
	v_mfma_f32_32x32x16_bf16 v[18:33], v[126:129], v[114:117], v[18:33]
	v_add_f32_e32 v254, v76, v254
	v_add_f32_e32 v255, v92, v255
	v_exp_f32_e32 v77, v77
	v_fma_f32 v112, v200, s76, v224
	v_fma_f32 v113, v200, s77, v224
	v_add_u32_e32 v179, v183, v208
	ds_read_b128 v[236:239], v179
	v_mfma_f32_32x32x16_bf16 v[2:17], v[118:121], v[114:117], v[2:17]
	v_add_f32_e64 v114, v240, v98
	v_add_f32_e64 v115, v240, v99
	v_add_f32_e64 v128, v240, v112
	v_add_f32_e64 v129, v240, v113
	v_add_f32_e64 v126, v240, v110
	v_add_f32_e64 v127, v240, v111
	v_add_f32_e32 v124, v240, v108
	v_add_f32_e32 v125, v240, v109
	v_add_f32_e32 v122, v240, v106
	v_add_f32_e32 v123, v240, v107
	v_add_f32_e32 v120, v240, v104
	v_add_f32_e32 v121, v240, v105
	v_add_f32_e32 v118, v240, v102
	v_add_f32_e32 v119, v240, v103
	v_add_f32_e32 v116, v240, v100
	v_add_f32_e32 v117, v240, v101
	ds_read_b128 v[240:243], v179 offset:4096
	s_waitcnt lgkmcnt(2)
	v_mfma_f32_32x32x16_bf16 v[98:113], v[232:235], v[130:133], v[98:113]
	v_add_f32_e32 v254, v77, v254
	v_exp_f32_e32 v93, v93
	v_exp_f32_e32 v78, v78
	v_add_u32_e32 v179, v183, v209
	ds_read_b128 v[232:235], v179
	v_mfma_f32_32x32x16_bf16 v[114:129], v[228:231], v[130:133], v[114:129]
	v_add_f32_e32 v255, v93, v255
	v_add_f32_e32 v254, v78, v254
	v_exp_f32_e32 v94, v94
	v_exp_f32_e32 v79, v79
	ds_read_b128 v[228:231], v179 offset:4096
	s_waitcnt lgkmcnt(2)
	v_mfma_f32_32x32x16_bf16 v[98:113], v[236:239], v[134:137], v[98:113]
	v_add_f32_e32 v255, v94, v255
	v_add_f32_e32 v254, v79, v254
	v_exp_f32_e32 v95, v95
	v_exp_f32_e32 v80, v80
	v_add_u32_e32 v179, v183, v226
	ds_read_b128 v[236:239], v179
	v_mfma_f32_32x32x16_bf16 v[114:129], v[240:243], v[134:137], v[114:129]
	v_add_f32_e32 v255, v95, v255
	v_add_f32_e32 v254, v80, v254
	v_exp_f32_e32 v96, v96
	v_exp_f32_e32 v81, v81
	ds_read_b128 v[240:243], v179 offset:4096
	s_waitcnt lgkmcnt(2)
	v_mfma_f32_32x32x16_bf16 v[98:113], v[232:235], v[138:141], v[98:113]
	v_add_f32_e32 v255, v96, v255
	v_add_f32_e32 v254, v81, v254
	v_exp_f32_e32 v97, v97
	v_mfma_f32_32x32x16_bf16 v[114:129], v[228:231], v[138:141], v[114:129]
	v_add_f32_e32 v255, v97, v255
	v_add_f32_e32 v254, v255, v254
	s_waitcnt lgkmcnt(0)
	v_mfma_f32_32x32x16_bf16 v[98:113], v[236:239], v[142:145], v[98:113]
	v_mfma_f32_32x32x16_bf16 v[114:129], v[240:243], v[142:145], v[114:129]
	s_cmp_lg_u32 s4, 0
	s_cbranch_scc0 .LBB0_471
	s_waitcnt vmcnt(8) lgkmcnt(0)
	s_barrier
	s_cmp_eq_u32 s100, 0
	s_cbranch_scc1 .Lattn_fair_a
	s_setprio 1

.LBB0_464:
	s_add_i32 s4, s62, 1
	s_cmp_lg_u32 s62, 2
	s_cselect_b32 s4, s4, 0
	s_add_i32 s5, s10, 1
	s_cmp_lg_u32 s10, 2
	s_cselect_b32 s5, s5, 0
	s_lshl_b32 s62, s5, 14
	v_add_u32_e32 v198, s62, v219
	v_cvt_pk_bf16_f32 v66, v66, v67
	v_cvt_pk_bf16_f32 v67, v68, v69
	v_cvt_pk_bf16_f32 v68, v70, v71
	v_add_u32_e32 v70, v198, v149
	v_cvt_pk_bf16_f32 v69, v82, v83
	v_cvt_pk_bf16_f32 v74, v74, v75
	v_cvt_pk_bf16_f32 v75, v76, v77
	v_cvt_pk_bf16_f32 v76, v78, v79
	v_cvt_pk_bf16_f32 v77, v80, v81
	ds_read_b128 v[78:81], v70 offset:49152
	ds_read_b128 v[82:85], v70 offset:53248
	ds_read_b128 v[86:89], v70 offset:57344
	ds_read_b128 v[228:231], v70 offset:61440
	s_lshl_b32 s10, s4, 14
	s_cmp_gt_i32 s34, s48
	s_waitcnt lgkmcnt(2)
	v_mfma_f32_32x32x16_bf16 v[50:65], v[78:81], v[66:69], v[50:65]
	v_add_u32_e32 v70, v198, v208
	ds_read_b128 v[78:81], v70 offset:49152
	v_mfma_f32_32x32x16_bf16 v[34:49], v[82:85], v[66:69], v[34:49]
	ds_read_b128 v[232:235], v70 offset:53248
	s_waitcnt lgkmcnt(2)
	v_mfma_f32_32x32x16_bf16 v[18:33], v[86:89], v[66:69], v[18:33]
	ds_read_b128 v[86:89], v70 offset:57344
	v_mfma_f32_32x32x16_bf16 v[2:17], v[228:231], v[66:69], v[2:17]
	ds_read_b128 v[82:85], v70 offset:61440
	s_waitcnt lgkmcnt(2)
	v_mfma_f32_32x32x16_bf16 v[50:65], v[78:81], v[74:77], v[50:65]
	v_add_u32_e32 v227, v198, v209
	ds_read_b128 v[78:81], v227 offset:49152
	v_mfma_f32_32x32x16_bf16 v[34:49], v[232:235], v[74:77], v[34:49]
	s_cselect_b32 s81, 0, 1
	s_cmp_lt_i32 s78, s39
	s_cselect_b64 vcc, -1, 0
	s_cselect_b32 s79, s78, s61
	v_cndmask_b32_e64 v228, -v201, v201, vcc
	s_add_i32 s79, s79, s33
	s_lshl_b32 s78, s79, 6
	s_cmp_lg_u32 s100, 0
	s_cbranch_scc1 .Lattn_dma_b
	s_lshl_b32 s84, s78, 1
	s_mov_b32 s85, 0
	s_addk_i32 s62, 0xc000
	s_cmp_lg_u32 s5, 0
	s_cselect_b32 s79, s62, 0x8000
	s_add_i32 s79, s14, s79
	v_lshl_add_u64 v[66:67], v[204:205], 0, s[84:85]
	s_add_i32 m0, s79, 0xc000
	v_lshl_add_u64 v[68:69], v[206:207], 0, s[84:85]
	global_load_lds_dwordx4 v[66:67], off
	s_add_i32 m0, s79, 0xc400
	s_mov_b32 s84, 0xc00000
	global_load_lds_dwordx4 v[68:69], off
	s_add_i32 m0, s79, 0xe000
	v_lshl_add_u64 v[66:67], v[66:67], 0, s[84:85]
	global_load_lds_dwordx4 v[66:67], off
	s_add_i32 m0, s79, 0xe400
	v_lshl_add_u64 v[68:69], v[68:69], 0, s[84:85]
	global_load_lds_dwordx4 v[68:69], off
	s_cmp_lg_u32 s81, 0
	s_cbranch_scc0 .Lattn_dma_b
	s_cmp_lt_i32 s61, s39
	s_movk_i32 s79, 0xc0
	s_cselect_b32 s79, s79, 0x140
	s_add_i32 s84, s60, s79
	s_lshl_b32 s84, s84, 12
	s_add_i32 s79, s10, 0xffffc000
	s_cmp_lg_u32 s4, 0
	s_cselect_b32 s79, s79, 0x8000
	v_lshl_add_u64 v[66:67], v[202:203], 0, s[84:85]
	s_add_i32 s79, s7, s79
	s_mov_b32 m0, s79
	v_lshl_add_u64 v[68:69], v[66:67], 0, s[30:31]
	global_load_lds_dwordx4 v[68:69], off
	s_add_i32 m0, s79, 0x2000
	v_lshl_add_u64 v[66:67], v[66:67], 0, s[36:37]
	global_load_lds_dwordx4 v[66:67], off
	s_mov_b32 s84, 0x20000
	s_add_i32 m0, s79, 0x1000
	v_lshl_add_u64 v[68:69], v[68:69], 0, s[84:85]
	global_load_lds_dwordx4 v[68:69], off
	s_add_i32 m0, s79, 0x3000
	v_lshl_add_u64 v[66:67], v[66:67], 0, s[84:85]
	global_load_lds_dwordx4 v[66:67], off
.Lattn_dma_b:
	v_cvt_f32_i32_e32 v66, s78
	v_exp_f32_e32 v231, v98
	v_add_f32_e32 v66, v155, v66
	v_fma_f32 v230, v228, v66, -v199
	v_add_u32_e32 v229, s10, v218
	v_exp_f32_e32 v233, v114
	v_fma_f32 v66, 0, v228, v230
	v_exp_f32_e32 v234, v99
	v_exp_f32_e32 v235, v115
	v_add_f32_e32 v67, v228, v230
	v_exp_f32_e32 v236, v100
	v_exp_f32_e32 v237, v116
	v_exp_f32_e32 v238, v101
	v_exp_f32_e32 v239, v117
	v_fma_f32 v68, v228, s64, v230
	v_fma_f32 v69, v228, s65, v230
	v_fma_f32 v70, v228, s66, v230
	v_fma_f32 v71, v228, s67, v230
	v_cvt_pk_bf16_f32 v98, v249, v250
	v_cvt_pk_bf16_f32 v99, v195, v251
	v_cvt_pk_bf16_f32 v100, v252, v253
	v_cvt_pk_bf16_f32 v101, v72, v73
	v_cvt_pk_bf16_f32 v114, v90, v91
	v_cvt_pk_bf16_f32 v115, v92, v93
	v_cvt_pk_bf16_f32 v116, v94, v95
	v_cvt_pk_bf16_f32 v117, v96, v97
	v_mul_f32_e32 v232, 0x42000000, v228
	v_exp_f32_e32 v240, v102
	v_exp_f32_e32 v241, v118
	v_exp_f32_e32 v242, v103
	v_exp_f32_e32 v243, v119
	ds_read_b128 v[90:93], v227 offset:53248
	s_waitcnt lgkmcnt(2)
	v_mfma_f32_32x32x16_bf16 v[18:33], v[86:89], v[74:77], v[18:33]
	v_add_f32_e32 v254, 0, v231
	v_add_f32_e32 v255, 0, v233
	v_fma_f32 v72, v228, s68, v230
	v_fma_f32 v73, v228, s69, v230
	v_exp_f32_e32 v181, v104
	v_exp_f32_e32 v183, v120
	ds_read_b128 v[86:89], v227 offset:57344
	v_mfma_f32_32x32x16_bf16 v[2:17], v[82:85], v[74:77], v[2:17]
	s_setprio 0
	v_add_f32_e32 v254, v234, v254
	v_add_f32_e32 v255, v235, v255
	v_exp_f32_e32 v195, v105
	v_exp_f32_e32 v200, v121
	ds_read_b128 v[82:85], v227 offset:61440
	s_waitcnt lgkmcnt(2)
	v_mfma_f32_32x32x16_bf16 v[50:65], v[78:81], v[98:101], v[50:65]
	v_add_f32_e32 v254, v236, v254
	v_add_f32_e32 v255, v237, v255
	v_fma_f32 v74, v228, s70, v230
	v_fma_f32 v75, v228, s71, v230
	v_exp_f32_e32 v224, v106
	v_exp_f32_e32 v122, v122
	v_add_u32_e32 v78, v198, v226
	ds_read_b128 v[94:97], v78 offset:49152
	v_mfma_f32_32x32x16_bf16 v[34:49], v[90:93], v[98:101], v[34:49]
	v_add_f32_e32 v254, v238, v254
	v_add_f32_e32 v255, v239, v255
	v_exp_f32_e32 v225, v107
	v_exp_f32_e32 v123, v123
	ds_read_b128 v[90:93], v78 offset:53248
	s_waitcnt lgkmcnt(2)
	v_mfma_f32_32x32x16_bf16 v[18:33], v[86:89], v[98:101], v[18:33]
	v_add_f32_e32 v254, v240, v254
	v_add_f32_e32 v255, v241, v255
	v_fma_f32 v76, v228, s72, v230
	v_fma_f32 v77, v228, s73, v230
	v_exp_f32_e32 v227, v108
	v_exp_f32_e32 v124, v124
	ds_read_b128 v[86:89], v78 offset:57344
	v_mfma_f32_32x32x16_bf16 v[2:17], v[82:85], v[98:101], v[2:17]
	v_add_f32_e32 v254, v242, v254
	v_add_f32_e32 v255, v243, v255
	v_exp_f32_e32 v244, v109
	v_exp_f32_e32 v125, v125
	ds_read_b128 v[98:101], v78 offset:61440
	s_waitcnt lgkmcnt(2)
	v_mfma_f32_32x32x16_bf16 v[50:65], v[94:97], v[114:117], v[50:65]
	v_add_f32_e32 v254, v181, v254
	v_add_f32_e32 v255, v183, v255
	v_fma_f32 v78, v228, s74, v230
	v_fma_f32 v79, v228, s75, v230
	v_exp_f32_e32 v245, v110
	v_exp_f32_e32 v126, v126
	v_add_u32_e32 v80, v229, v149
	ds_read_b128 v[102:105], v80
	v_mfma_f32_32x32x16_bf16 v[34:49], v[90:93], v[114:117], v[34:49]
	v_add_f32_e32 v254, v195, v254
	v_add_f32_e32 v255, v200, v255
	v_exp_f32_e32 v246, v111
	v_exp_f32_e32 v127, v127
	ds_read_b128 v[106:109], v80 offset:4096
	s_waitcnt lgkmcnt(2)
	v_mfma_f32_32x32x16_bf16 v[18:33], v[86:89], v[114:117], v[18:33]
	v_add_f32_e32 v254, v224, v254
	v_add_f32_e32 v255, v122, v255
	v_fma_f32 v80, v228, s76, v230
	v_fma_f32 v81, v228, s77, v230
	v_exp_f32_e32 v247, v112
	v_exp_f32_e32 v128, v128
	v_add_u32_e32 v110, v229, v208
	ds_read_b128 v[118:121], v110
	v_mfma_f32_32x32x16_bf16 v[2:17], v[98:101], v[114:117], v[2:17]
	v_add_f32_e32 v254, v225, v254
	v_add_f32_e32 v255, v123, v255
	v_add_f32_e64 v82, v232, v66
	v_add_f32_e64 v83, v232, v67
	v_add_f32_e64 v96, v232, v80
	v_add_f32_e64 v97, v232, v81
	v_add_f32_e64 v94, v232, v78
	v_add_f32_e64 v95, v232, v79
	v_add_f32_e32 v92, v232, v76
	v_add_f32_e32 v93, v232, v77
	v_add_f32_e32 v90, v232, v74
	v_add_f32_e32 v91, v232, v75
	v_add_f32_e32 v88, v232, v72
	v_add_f32_e32 v89, v232, v73
	v_add_f32_e32 v86, v232, v70
	v_add_f32_e32 v87, v232, v71
	v_add_f32_e32 v84, v232, v68
	v_add_f32_e32 v85, v232, v69
	v_exp_f32_e32 v228, v113
	v_exp_f32_e32 v129, v129
	ds_read_b128 v[98:101], v110 offset:4096
	s_waitcnt lgkmcnt(2)
	v_mfma_f32_32x32x16_bf16 v[66:81], v[102:105], v[130:133], v[66:81]
	v_add_f32_e32 v254, v227, v254
	v_add_f32_e32 v255, v124, v255
	v_add_f32_e32 v254, v244, v254
	v_add_u32_e32 v110, v229, v209
	ds_read_b128 v[102:105], v110
	v_mfma_f32_32x32x16_bf16 v[82:97], v[106:109], v[130:133], v[82:97]
	v_add_f32_e32 v255, v125, v255
	v_add_f32_e32 v254, v245, v254
	v_add_f32_e32 v255, v126, v255
	ds_read_b128 v[106:109], v110 offset:4096
	s_waitcnt lgkmcnt(2)
	v_mfma_f32_32x32x16_bf16 v[66:81], v[118:121], v[134:137], v[66:81]
	v_add_f32_e32 v254, v246, v254
	v_add_f32_e32 v255, v127, v255
	v_add_f32_e32 v254, v247, v254
	v_add_u32_e32 v114, v229, v226
	ds_read_b128 v[110:113], v114
	v_mfma_f32_32x32x16_bf16 v[82:97], v[98:101], v[134:137], v[82:97]
	v_add_f32_e32 v255, v128, v255
	v_add_f32_e32 v254, v228, v254
	v_add_f32_e32 v255, v129, v255
	v_add_f32_e32 v254, v255, v254
	ds_read_b128 v[98:101], v114 offset:4096
	s_waitcnt lgkmcnt(2)
	v_mfma_f32_32x32x16_bf16 v[66:81], v[102:105], v[138:141], v[66:81]
	v_cvt_pk_bf16_f32 v114, v122, v123
	v_cvt_pk_bf16_f32 v115, v124, v125
	v_cvt_pk_bf16_f32 v116, v126, v127
	v_cvt_pk_bf16_f32 v117, v128, v129
	v_mfma_f32_32x32x16_bf16 v[82:97], v[106:109], v[138:141], v[82:97]
	v_cvt_pk_bf16_f32 v106, v224, v225
	v_cvt_pk_bf16_f32 v107, v227, v244
	v_cvt_pk_bf16_f32 v108, v245, v246
	v_cvt_pk_bf16_f32 v109, v247, v228
	s_waitcnt lgkmcnt(0)
	v_mfma_f32_32x32x16_bf16 v[66:81], v[110:113], v[142:145], v[66:81]
	v_cvt_pk_bf16_f32 v110, v233, v235
	v_cvt_pk_bf16_f32 v111, v237, v239
	v_cvt_pk_bf16_f32 v112, v241, v243
	v_cvt_pk_bf16_f32 v113, v183, v200
	v_mfma_f32_32x32x16_bf16 v[82:97], v[98:101], v[142:145], v[82:97]
	s_add_i32 s10, s4, 1
	s_cmp_lg_u32 s4, 2
	s_cselect_b32 s62, s10, 0
	s_add_i32 s4, s5, 1
	s_cmp_lg_u32 s5, 2
	s_cselect_b32 s10, s4, 0
	s_add_i32 s34, s34, 2
	v_add_f32_e32 v198, v179, v254
	v_cvt_pk_bf16_f32 v98, v231, v234
	v_cvt_pk_bf16_f32 v99, v236, v238
	v_cvt_pk_bf16_f32 v100, v240, v242
	v_cvt_pk_bf16_f32 v101, v181, v195
	s_cmp_ge_i32 s61, s48
	s_cbranch_scc1 .LBB0_473
	s_mov_b32 s60, s63
	s_add_i32 s61, s34, -2
	s_cmp_gt_i32 s61, s48
	s_cbranch_scc1 .LBB0_469
.LBB0_468:
	s_waitcnt vmcnt(8) lgkmcnt(0)
	s_barrier
	s_cmp_eq_u32 s100, 0
	s_cbranch_scc1 .Lattn_fair_0
	s_setprio 1
.Lattn_fair_0:
	s_cmp_lg_u32 s99, 0
	s_cbranch_scc1 .Lattn_A_fast
	s_branch .LBB0_452
.LBB0_469:
	s_waitcnt vmcnt(4) lgkmcnt(0)
	s_barrier
	s_cmp_eq_u32 s100, 0
	s_cbranch_scc1 .Lattn_fair_1
	s_setprio 1
.Lattn_fair_1:
	s_andn2_b64 vcc, exec, s[2:3]
	s_cbranch_vccz .LBB0_453
	s_branch .LBB0_454
.LBB0_471:
	s_mov_b64 s[4:5], -1
	s_waitcnt vmcnt(4) lgkmcnt(0)
	s_barrier
	s_cmp_eq_u32 s100, 0
	s_cbranch_scc1 .Lattn_fair_3
	s_setprio 1

.LBB0_473:
	s_waitcnt vmcnt(4) lgkmcnt(0)
	s_barrier
	s_andn2_b64 vcc, exec, s[2:3]
	s_cbranch_vccnz .LBB0_475
	v_pk_mul_f32 v[64:65], v[64:65], v[0:1] op_sel_hi:[1,0]
	v_pk_mul_f32 v[62:63], v[62:63], v[0:1] op_sel_hi:[1,0]
	v_pk_mul_f32 v[60:61], v[60:61], v[0:1] op_sel_hi:[1,0]
	v_pk_mul_f32 v[58:59], v[58:59], v[0:1] op_sel_hi:[1,0]
	v_pk_mul_f32 v[56:57], v[56:57], v[0:1] op_sel_hi:[1,0]
	v_pk_mul_f32 v[54:55], v[54:55], v[0:1] op_sel_hi:[1,0]
	v_pk_mul_f32 v[52:53], v[52:53], v[0:1] op_sel_hi:[1,0]
	v_pk_mul_f32 v[50:51], v[50:51], v[0:1] op_sel_hi:[1,0]
	v_pk_mul_f32 v[48:49], v[48:49], v[0:1] op_sel_hi:[1,0]
	v_pk_mul_f32 v[46:47], v[46:47], v[0:1] op_sel_hi:[1,0]
	v_pk_mul_f32 v[44:45], v[44:45], v[0:1] op_sel_hi:[1,0]
	v_pk_mul_f32 v[42:43], v[42:43], v[0:1] op_sel_hi:[1,0]
	v_pk_mul_f32 v[40:41], v[40:41], v[0:1] op_sel_hi:[1,0]
	v_pk_mul_f32 v[38:39], v[38:39], v[0:1] op_sel_hi:[1,0]
	v_pk_mul_f32 v[36:37], v[36:37], v[0:1] op_sel_hi:[1,0]
	v_pk_mul_f32 v[34:35], v[34:35], v[0:1] op_sel_hi:[1,0]
	v_pk_mul_f32 v[32:33], v[32:33], v[0:1] op_sel_hi:[1,0]
	v_pk_mul_f32 v[30:31], v[30:31], v[0:1] op_sel_hi:[1,0]
	v_pk_mul_f32 v[28:29], v[28:29], v[0:1] op_sel_hi:[1,0]
	v_pk_mul_f32 v[26:27], v[26:27], v[0:1] op_sel_hi:[1,0]
	v_pk_mul_f32 v[24:25], v[24:25], v[0:1] op_sel_hi:[1,0]
	v_pk_mul_f32 v[22:23], v[22:23], v[0:1] op_sel_hi:[1,0]
	v_pk_mul_f32 v[20:21], v[20:21], v[0:1] op_sel_hi:[1,0]
	v_pk_mul_f32 v[18:19], v[18:19], v[0:1] op_sel_hi:[1,0]
	v_pk_mul_f32 v[16:17], v[16:17], v[0:1] op_sel_hi:[1,0]
	v_pk_mul_f32 v[14:15], v[14:15], v[0:1] op_sel_hi:[1,0]
	v_pk_mul_f32 v[12:13], v[12:13], v[0:1] op_sel_hi:[1,0]
	v_pk_mul_f32 v[10:11], v[10:11], v[0:1] op_sel_hi:[1,0]
	v_pk_mul_f32 v[8:9], v[8:9], v[0:1] op_sel_hi:[1,0]
	v_pk_mul_f32 v[6:7], v[6:7], v[0:1] op_sel_hi:[1,0]
	v_pk_mul_f32 v[4:5], v[4:5], v[0:1] op_sel_hi:[1,0]
	v_pk_mul_f32 v[2:3], v[2:3], v[0:1] op_sel_hi:[1,0]
	v_mov_b32_e32 v0, 1.0
